# speedup vs baseline: 1.0275x; 1.0275x over previous
_Z4mega6Params:
	s_mov_b32 s101, 1
	s_load_dwordx16 s[52:67], s[0:1], 0x0
	s_load_dwordx4 s[84:87], s[0:1], 0xc0
	s_load_dwordx2 s[6:7], s[0:1], 0xd0
	s_load_dwordx16 s[8:23], s[0:1], 0x40
	s_load_dwordx16 s[36:51], s[0:1], 0x80
	s_mov_b64 s[92:93], s[0:1]
	s_waitcnt lgkmcnt(0)
	s_cmpk_lt_i32 s7, 0x3e9
	v_writelane_b32 v252, s8, 0
	s_nop 1
	v_writelane_b32 v252, s9, 1
	v_writelane_b32 v252, s10, 2
	v_writelane_b32 v252, s11, 3
	v_writelane_b32 v252, s12, 4
	v_writelane_b32 v252, s13, 5
	v_writelane_b32 v252, s14, 6
	v_writelane_b32 v252, s15, 7
	v_writelane_b32 v252, s16, 8
	v_writelane_b32 v252, s17, 9
	v_writelane_b32 v252, s18, 10
	v_writelane_b32 v252, s19, 11
	v_writelane_b32 v252, s20, 12
	v_writelane_b32 v252, s21, 13
	v_writelane_b32 v252, s22, 14
	v_writelane_b32 v252, s23, 15
	v_writelane_b32 v252, s6, 16
	s_nop 1
	v_writelane_b32 v252, s7, 17
	s_cbranch_scc1 .LBB0_12
	v_and_b32_e32 v1, 0x3fffffff, v0
	v_cmp_eq_u32_e32 vcc, 0, v1
	s_barrier
	s_and_saveexec_b64 s[0:1], vcc
	s_cbranch_execz .LBB0_11
	buffer_wbl2 sc1
	s_load_dwordx2 s[4:5], s[92:93], 0x130
	s_mov_b64 s[6:7], exec
	v_mbcnt_lo_u32_b32 v1, s6, 0
	v_mbcnt_hi_u32_b32 v1, s7, v1
	v_cmp_eq_u32_e32 vcc, 0, v1
	s_waitcnt lgkmcnt(0)
	s_load_dword s3, s[4:5], 0x28
	s_and_saveexec_b64 s[8:9], vcc
	s_cbranch_execz .LBB0_4
	s_bcnt1_i32_b64 s6, s[6:7]
	v_mov_b32_e32 v2, 0
	v_mov_b32_e32 v3, s6
	global_atomic_add v2, v2, v3, s[4:5] offset:32 sc0

.LBB0_223:
	s_waitcnt vmcnt(0)
	s_add_u32 s88, s86, 0x2b00000
	s_addc_u32 s89, s87, 0
	v_cmp_eq_u32_e32 vcc, 0, v1
	s_barrier
	s_and_saveexec_b64 s[0:1], vcc
	v_readlane_b32 s92, v252, 18
	v_readlane_b32 s93, v252, 19
	s_cbranch_execz .LBB0_243
	s_getreg_b32 s3, hwreg(HW_REG_XCC_ID, 0, 4)
	s_mov_b64 s[6:7], exec
	s_and_b32 s3, s3, 15
	s_nop 4
	s_lshl_b32 s99, 1, s3
	s_and_b32 s98, s2, 7
	s_lshl_b32 s98, s98, 2
	v_mov_b32_e32 v1, s98
	v_mov_b32_e32 v2, s99
	global_atomic_or v1, v2, s[88:89] offset:768
	s_lshl_b32 s4, s3, 8
	v_mbcnt_lo_u32_b32 v1, s6, 0
	s_add_u32 s4, s88, s4
	v_mbcnt_hi_u32_b32 v1, s7, v1
	s_addc_u32 s5, s89, 0
	v_cmp_eq_u32_e32 vcc, 0, v1
	s_and_saveexec_b64 s[8:9], vcc
	s_cbranch_execz .LBB0_226
	s_bcnt1_i32_b64 s6, s[6:7]
	v_mov_b32_e32 v1, 0
	v_mov_b32_e32 v2, s6
	global_atomic_add v1, v2, s[4:5] offset:1024

.LBB0_242:
	s_or_b64 exec, exec, s[6:7]
	v_mov_b32_e32 v1, 0x2b00000
	buffer_wbl2 sc1
	s_waitcnt vmcnt(0)
	buffer_inv sc1
	global_load_dword v2, v1, s[86:87] offset:1024 sc1
	global_load_dword v4, v1, s[86:87] offset:1280 sc1
	global_load_dword v6, v1, s[86:87] offset:1536 sc1
	global_load_dword v7, v1, s[86:87] offset:1792 sc1
	global_load_dword v8, v1, s[86:87] offset:2048 sc1
	global_load_dword v9, v1, s[86:87] offset:2304 sc1
	global_load_dword v10, v1, s[86:87] offset:2560 sc1
	global_load_dword v11, v1, s[86:87] offset:2816 sc1
	global_load_dword v12, v1, s[86:87] offset:3072 sc1
	global_load_dword v13, v1, s[86:87] offset:3328 sc1
	global_load_dword v14, v1, s[86:87] offset:3584 sc1
	global_load_dword v15, v1, s[86:87] offset:3840 sc1
	v_mov_b32_e32 v1, 0x2b01000
	global_load_dword v16, v1, s[86:87] sc1
	global_load_dword v17, v1, s[86:87] offset:256 sc1
	global_load_dword v18, v1, s[86:87] offset:512 sc1
	global_load_dword v19, v1, s[86:87] offset:768 sc1
	v_mov_b32_e32 v5, 0
	global_load_dword v3, v5, s[4:5] offset:1024 sc1
	global_load_dwordx4 v[20:23], v5, s[88:89] offset:768 sc1
	global_load_dwordx4 v[24:27], v5, s[88:89] offset:784 sc1
	s_load_dword s100, s[92:93], 0xd8
	s_waitcnt vmcnt(16)
	v_cmp_ne_u32_e32 vcc, 0, v2
	s_nop 1
	v_cndmask_b32_e64 v1, 0, 1, vcc
	s_waitcnt vmcnt(14)
	v_cmp_ne_u32_e32 vcc, 0, v6
	s_nop 1
	v_cndmask_b32_e64 v2, 0, 1, vcc
	s_waitcnt vmcnt(12)
	v_cmp_ne_u32_e32 vcc, 0, v8
	s_nop 1
	v_cndmask_b32_e64 v6, 0, 1, vcc
	s_waitcnt vmcnt(10)
	v_cmp_ne_u32_e32 vcc, 0, v10
	s_nop 1
	v_cndmask_b32_e64 v8, 0, 1, vcc
	s_waitcnt vmcnt(8)
	v_cmp_ne_u32_e32 vcc, 0, v12
	s_nop 1
	v_cndmask_b32_e64 v10, 0, 1, vcc
	s_waitcnt vmcnt(6)
	v_cmp_ne_u32_e32 vcc, 0, v14
	s_nop 1
	v_cndmask_b32_e64 v12, 0, 1, vcc
	s_waitcnt vmcnt(4)
	v_cmp_ne_u32_e32 vcc, 0, v16
	s_nop 1
	v_cndmask_b32_e64 v14, 0, 1, vcc
	s_waitcnt vmcnt(2)
	v_cmp_ne_u32_e32 vcc, 0, v18
	s_nop 1
	v_cndmask_b32_e64 v16, 0, 1, vcc
	v_cmp_ne_u32_e32 vcc, 0, v4
	s_nop 1
	v_addc_co_u32_e32 v1, vcc, 0, v1, vcc
	v_cmp_ne_u32_e32 vcc, 0, v7
	s_nop 1
	v_addc_co_u32_e32 v1, vcc, v1, v2, vcc
	v_cmp_ne_u32_e32 vcc, 0, v9
	v_mov_b32_e32 v2, s3
	s_nop 0
	v_addc_co_u32_e32 v1, vcc, v1, v6, vcc
	v_cmp_ne_u32_e32 vcc, 0, v11
	s_nop 1
	v_addc_co_u32_e32 v1, vcc, v1, v8, vcc
	v_cmp_ne_u32_e32 vcc, 0, v13
	s_nop 1
	v_addc_co_u32_e32 v1, vcc, v1, v10, vcc
	v_cmp_ne_u32_e32 vcc, 0, v15
	s_nop 1
	v_addc_co_u32_e32 v1, vcc, v1, v12, vcc
	v_cmp_ne_u32_e32 vcc, 0, v17
	s_nop 1
	v_addc_co_u32_e32 v1, vcc, v1, v14, vcc
	s_waitcnt vmcnt(1)
	v_cmp_ne_u32_e32 vcc, 0, v19
	s_nop 1
	v_addc_co_u32_e32 v4, vcc, v1, v16, vcc
	s_waitcnt vmcnt(0)
	v_add_u32_e32 v28, -1, v20
	v_and_b32_e32 v28, v28, v20
	v_cmp_eq_u32_e32 vcc, 0, v20
	s_nop 1
	v_cndmask_b32_e64 v29, 0, 1, vcc
	v_or_b32_e32 v28, v28, v29
	v_mov_b32_e32 v30, v28
	v_add_u32_e32 v28, -1, v21
	v_and_b32_e32 v28, v28, v21
	v_cmp_eq_u32_e32 vcc, 0, v21
	s_nop 1
	v_cndmask_b32_e64 v29, 0, 1, vcc
	v_or_b32_e32 v28, v28, v29
	v_or_b32_e32 v30, v30, v28
	v_add_u32_e32 v28, -1, v22
	v_and_b32_e32 v28, v28, v22
	v_cmp_eq_u32_e32 vcc, 0, v22
	s_nop 1
	v_cndmask_b32_e64 v29, 0, 1, vcc
	v_or_b32_e32 v28, v28, v29
	v_or_b32_e32 v30, v30, v28
	v_add_u32_e32 v28, -1, v23
	v_and_b32_e32 v28, v28, v23
	v_cmp_eq_u32_e32 vcc, 0, v23
	s_nop 1
	v_cndmask_b32_e64 v29, 0, 1, vcc
	v_or_b32_e32 v28, v28, v29
	v_or_b32_e32 v30, v30, v28
	v_add_u32_e32 v28, -1, v24
	v_and_b32_e32 v28, v28, v24
	v_cmp_eq_u32_e32 vcc, 0, v24
	s_nop 1
	v_cndmask_b32_e64 v29, 0, 1, vcc
	v_or_b32_e32 v28, v28, v29
	v_or_b32_e32 v30, v30, v28
	v_add_u32_e32 v28, -1, v25
	v_and_b32_e32 v28, v28, v25
	v_cmp_eq_u32_e32 vcc, 0, v25
	s_nop 1
	v_cndmask_b32_e64 v29, 0, 1, vcc
	v_or_b32_e32 v28, v28, v29
	v_or_b32_e32 v30, v30, v28
	v_add_u32_e32 v28, -1, v26
	v_and_b32_e32 v28, v28, v26
	v_cmp_eq_u32_e32 vcc, 0, v26
	s_nop 1
	v_cndmask_b32_e64 v29, 0, 1, vcc
	v_or_b32_e32 v28, v28, v29
	v_or_b32_e32 v30, v30, v28
	v_add_u32_e32 v28, -1, v27
	v_and_b32_e32 v28, v28, v27
	v_cmp_eq_u32_e32 vcc, 0, v27
	s_nop 1
	v_cndmask_b32_e64 v29, 0, 1, vcc
	v_or_b32_e32 v28, v28, v29
	v_or_b32_e32 v30, v30, v28
	s_waitcnt lgkmcnt(0)
	s_nop 0
	v_readfirstlane_b32 s101, v30
	s_and_b32 s98, s100, 7
	s_lshr_b32 s100, s100, 3
	s_nop 1
	s_or_b32 s101, s101, s98
	ds_write_b128 v5, v[2:5]

.LBB0_331:
	s_cbranch_execz .LBB0_249
	v_readlane_b32 s34, v252, 16
	v_readlane_b32 s35, v252, 17
	s_cmp_lt_i32 s35, 2
	s_cbranch_scc1 .LBB0_371
	s_waitcnt vmcnt(0)
	v_cmp_eq_u32_e32 vcc, 0, v1
	s_waitcnt vmcnt(0)
	s_barrier
	s_and_saveexec_b64 s[0:1], vcc
	s_cbranch_execz .LBB0_370
	s_cmp_lg_u32 s101, 0
	s_cbranch_scc1 .Lxl_glob_1
	s_and_b32 s6, s2, 7
	v_mov_b32_e32 v2, 0
	v_mov_b32_e32 v3, 1
	s_nop 3
	s_lshl_b32 s3, s6, 8
	s_add_u32 s4, s86, s3
	s_addc_u32 s5, s87, 0
	s_add_u32 s4, s4, 0x2b00480
	s_addc_u32 s5, s5, 0
	s_mov_b32 s98, 0
	global_atomic_add v2, v3, s[4:5]
.Lxl_spin_1:
	s_add_u32 s98, s98, 1
	s_cmp_lt_u32 s98, 0x40000
	s_cbranch_scc0 .Lxl_exit_1
	s_sleep 1
	global_load_dword v3, v2, s[4:5] sc1
	s_waitcnt vmcnt(0)
	v_cmp_gt_u32_e32 vcc, s100, v3
	s_cbranch_vccnz .Lxl_spin_1
.Lxl_exit_1:
	buffer_inv sc1
	s_branch .LBB0_370
.Lxl_glob_1:
	s_mov_b64 s[4:5], exec
	v_mbcnt_lo_u32_b32 v1, s4, 0
	v_readlane_b32 s6, v252, 20
	v_mbcnt_hi_u32_b32 v1, s5, v1
	v_readlane_b32 s7, v252, 21
	s_lshl_b32 s3, s6, 6
	v_cmp_eq_u32_e32 vcc, 0, v1
	s_waitcnt vmcnt(0) expcnt(0) lgkmcnt(0)
	s_and_saveexec_b64 s[6:7], vcc
	s_cbranch_execz .LBB0_336
	s_add_i32 s8, s3, 0x500
	s_mov_b32 s9, 0
	s_lshl_b64 s[8:9], s[8:9], 2
	s_add_u32 s8, s88, s8
	s_addc_u32 s9, s89, s9
	s_bcnt1_i32_b64 s4, s[4:5]
	v_mov_b32_e32 v2, 0
	v_mov_b32_e32 v3, s4
	global_atomic_add v2, v2, v3, s[8:9] sc0

.LBB0_550:
	s_cbranch_execz .LBB0_539
	v_readlane_b32 s34, v252, 16
	v_readlane_b32 s35, v252, 17
	s_cmp_lt_i32 s35, 5
	s_cbranch_scc1 .LBB0_590
	s_waitcnt vmcnt(0)
	v_cmp_eq_u32_e32 vcc, 0, v1
	s_waitcnt vmcnt(0)
	s_barrier
	s_and_saveexec_b64 s[0:1], vcc
	s_cbranch_execz .LBB0_589
	s_cmp_lg_u32 s101, 0
	s_cbranch_scc1 .Lxl_glob_4
	s_and_b32 s6, s2, 7
	v_mov_b32_e32 v2, 0
	v_mov_b32_e32 v3, 1
	s_nop 3
	s_lshl_b32 s3, s6, 8
	s_add_u32 s4, s86, s3
	s_addc_u32 s5, s87, 0
	s_add_u32 s4, s4, 0x2b00484
	s_addc_u32 s5, s5, 0
	s_mov_b32 s98, 0
	global_atomic_add v2, v3, s[4:5]

.LBB0_620:
	s_cbranch_execz .LBB0_593
	v_readlane_b32 s34, v252, 16
	v_readlane_b32 s35, v252, 17
	s_cmp_lt_i32 s35, 6
	s_cbranch_scc1 .LBB0_660
	s_waitcnt vmcnt(0)
	v_cmp_eq_u32_e32 vcc, 0, v1
	s_waitcnt vmcnt(0) lgkmcnt(0)
	s_barrier
	s_and_saveexec_b64 s[0:1], vcc
	s_cbranch_execz .LBB0_659
	s_cmp_lg_u32 s101, 0
	s_cbranch_scc1 .Lxl_glob_5
	s_and_b32 s6, s2, 7
	v_mov_b32_e32 v2, 0
	v_mov_b32_e32 v3, 1
	s_nop 3
	s_lshl_b32 s3, s6, 8
	s_add_u32 s4, s86, s3
	s_addc_u32 s5, s87, 0
	s_add_u32 s4, s4, 0x2b00488
	s_addc_u32 s5, s5, 0
	s_mov_b32 s98, 0
	global_atomic_add v2, v3, s[4:5]

.LBB0_669:
	v_readlane_b32 s34, v252, 16
	v_readlane_b32 s35, v252, 17
	s_cmp_lt_i32 s35, 7
	s_cbranch_scc1 .LBB0_708
	s_waitcnt vmcnt(0)
	v_cmp_eq_u32_e32 vcc, 0, v1
	s_waitcnt vmcnt(0)
	s_barrier
	s_and_saveexec_b64 s[0:1], vcc
	s_cbranch_execz .LBB0_707
	s_cmp_lg_u32 s101, 0
	s_cbranch_scc1 .Lxl_glob_6
	s_and_b32 s6, s2, 7
	v_mov_b32_e32 v2, 0
	v_mov_b32_e32 v3, 1
	s_nop 3
	s_lshl_b32 s3, s6, 8
	s_add_u32 s4, s86, s3
	s_addc_u32 s5, s87, 0
	s_add_u32 s4, s4, 0x2b0048c
	s_addc_u32 s5, s5, 0
	s_mov_b32 s98, 0
	global_atomic_add v2, v3, s[4:5]

.LBB0_1001:
	s_cmp_gt_i32 s34, 9
	s_cselect_b64 s[0:1], -1, 0
	s_cmp_lt_i32 s35, 9
	s_cselect_b64 s[4:5], -1, 0
	s_or_b64 s[0:1], s[0:1], s[4:5]
	s_and_b64 vcc, exec, s[0:1]
	s_cbranch_vccnz .LBB0_1066
	s_mov_b64 s[0:1], 0
	s_load_dword s3, s[92:93], 0xd8
	v_mbcnt_lo_u32_b32 v2, -1, 0
	s_mov_b32 s1, 0
	v_and_b32_e32 v1, 0x3ff, v0
	s_waitcnt lgkmcnt(0)
	v_mov_b32_e32 v3, 0
	s_and_b32 s0, s3, 7
	s_cmp_lg_u32 s0, 0
	s_cselect_b64 s[4:5], -1, 0
	s_cmp_lt_i32 s3, 8
	s_cselect_b64 s[6:7], -1, 0
	s_lshl_b32 s0, s2, 8
	s_lshr_b32 s33, s3, 3
	s_or_b64 s[12:13], s[6:7], s[4:5]
	s_ashr_i32 s38, s2, 3
	s_and_b32 s39, s0, 0x700
	s_mov_b64 s[14:15], 0x4c00000
	s_mov_b32 s40, 0x4c00000
	s_movk_i32 s41, 0x70
	s_mov_b64 s[16:17], 0x2c00000
	s_mov_b64 s[18:19], 0x8c00000
	s_mov_b32 s44, 0x42f00000
	s_mov_b64 s[20:21], 0xac00000
	s_mov_b32 s45, 0xac00000
	s_mov_b64 s[22:23], 0x6c00000
	s_mov_b32 s46, 0x6c00000
	v_mov_b32_e32 v42, 0xff61b1e6
	v_mbcnt_hi_u32_b32 v43, -1, v2
	s_mov_b32 s47, 0
	s_mov_b32 s55, 0
	s_branch .LBB0_1004

.LBB0_1009:
	s_mov_b64 s[4:5], 0
	s_add_u32 s24, s86, s4
	s_addc_u32 s25, s87, s5
	v_mov_b32_e32 v51, v1
	s_lshr_b32 s4, s26, 4
	s_lshr_b32 s0, s26, 10
	s_and_b32 s4, s4, 48
	s_and_b32 s27, s26, 15
	v_ashrrev_i32_e32 v12, 3, v51
	s_or_b32 s10, s4, s27
	s_lshl_b64 s[4:5], s[0:1], 13
	v_ashrrev_i32_e32 v13, 31, v12
	s_lshl_b32 s6, s26, 2
	v_lshl_add_u64 v[4:5], s[4:5], 0, v[12:13]
	s_and_b32 s48, s6, 0x3c0
	v_lshlrev_b64 v[4:5], 11, v[4:5]
	s_lshl_b32 s6, s48, 1
	s_mov_b32 s7, s1
	v_lshl_add_u64 v[4:5], s[24:25], 0, v[4:5]
	v_lshlrev_b32_e32 v2, 4, v51
	v_lshl_add_u64 v[4:5], v[4:5], 0, s[6:7]
	v_and_b32_e32 v6, 0x70, v2
	v_mov_b32_e32 v7, v3
	v_lshl_add_u64 v[4:5], v[4:5], 0, v[6:7]
	v_lshl_add_u64 v[36:37], v[4:5], 0, s[16:17]
	v_add_u32_e32 v4, s48, v12
	v_ashrrev_i32_e32 v5, 31, v4
	v_lshlrev_b64 v[4:5], 15, v[4:5]
	v_lshl_add_u64 v[4:5], s[24:25], 0, v[4:5]
	s_lshl_b64 s[8:9], s[0:1], 14
	s_lshl_b32 s0, s10, 1
	v_lshl_add_u64 v[4:5], v[4:5], 0, s[8:9]
	s_or_b32 s28, s0, 1
	v_ashrrev_i32_e32 v13, 6, v51
	v_lshl_add_u64 v[4:5], v[4:5], 0, v[6:7]
	s_lshl_b32 s0, s28, 17
	v_and_b32_e32 v53, 15, v51
	v_lshlrev_b32_e32 v48, 4, v13
	v_lshl_add_u64 v[38:39], v[4:5], 0, s[18:19]
	v_lshl_add_u64 v[4:5], v[36:37], 0, s[0:1]
	s_lshl_b32 s0, s28, 7
	v_or_b32_e32 v54, v48, v53
	s_lshl_b32 s8, s10, 7
	v_lshl_add_u64 v[8:9], v[38:39], 0, s[0:1]
	v_add_u32_e32 v14, s8, v54
	v_mov_b64_e32 v[110:111], v[4:5]
	s_nop 0
	v_mov_b64_e32 v[112:113], v[8:9]
	v_ashrrev_i32_e32 v15, 31, v14
	v_lshl_add_u64 v[14:15], s[4:5], 0, v[14:15]
	v_lshlrev_b64 v[16:17], 11, v[14:15]
	v_lshl_add_u64 v[16:17], s[24:25], 0, v[16:17]
	v_lshl_add_u64 v[16:17], v[16:17], 0, s[6:7]
	v_and_b32_e32 v2, 48, v51
	v_lshl_add_u64 v[16:17], v[16:17], 0, v[2:3]
	v_lshl_add_u64 v[18:19], v[16:17], 0, s[14:15]
	v_add_co_u32_e32 v16, vcc, s40, v16
	s_lshl_b32 s0, s10, 18
	s_nop 0
	v_addc_co_u32_e32 v17, vcc, 0, v17, vcc
	v_mov_b64_e32 v[114:115], v[16:17]
	v_mov_b64_e32 v[116:117], v[18:19]
	v_lshl_add_u64 v[16:17], v[36:37], 0, s[0:1]
	s_lshl_b32 s0, s10, 8
	s_cmp_eq_u32 s55, 0
	s_cbranch_scc1 .Lat_doload
	s_waitcnt vmcnt(0)
	v_mov_b32_e32 v4, v118
	v_mov_b32_e32 v5, v119
	v_mov_b32_e32 v6, v120
	v_mov_b32_e32 v7, v121
	v_mov_b32_e32 v8, v122
	v_mov_b32_e32 v9, v123
	v_mov_b32_e32 v10, v124
	v_mov_b32_e32 v11, v125
	v_mov_b32_e32 v20, v126
	v_mov_b32_e32 v21, v127
	v_mov_b32_e32 v22, v128
	v_mov_b32_e32 v23, v129
	v_mov_b32_e32 v24, v130
	v_mov_b32_e32 v25, v131
	v_mov_b32_e32 v26, v132
	v_mov_b32_e32 v27, v133
	s_branch .Lat_loaded
.Lat_doload:
	global_load_dwordx4 v[4:7], v[110:111], off
	global_load_dwordx4 v[8:11], v[112:113], off
	global_load_dwordx4 v[20:23], v[114:115], off
	global_load_dwordx4 v[24:27], v[116:117], off offset:64
.Lat_loaded:
	s_waitcnt vmcnt(0)
	s_barrier
	v_lshl_add_u64 v[18:19], v[38:39], 0, s[0:1]
	global_load_dwordx4 v[28:31], v[16:17], off
	global_load_dwordx4 v[32:35], v[18:19], off
	v_lshrrev_b32_e32 v17, 1, v51
	v_ashrrev_i32_e32 v18, 5, v51
	v_and_b32_e32 v17, 48, v17
	v_and_b32_e32 v18, -4, v18
	v_and_b32_e32 v19, 3, v12
	v_lshlrev_b32_e32 v40, 7, v12
	v_xor_b32_e32 v12, v12, v51
	v_add_u32_e32 v17, v17, v18
	v_lshlrev_b32_e32 v12, 4, v12
	v_or_b32_e32 v18, v17, v19
	v_bitop3_b32 v17, v17, v51, v19 bitop3:0x36
	v_and_or_b32 v45, v12, s41, v40
	v_lshlrev_b32_e32 v12, 7, v18
	v_lshlrev_b32_e32 v17, 4, v17
	v_and_or_b32 v46, v17, s41, v12
	v_bfe_u32 v44, v51, 4, 2
	v_add_u32_e32 v12, 0, v46
	v_add_u32_e32 v18, 0, v45
	v_and_b32_e32 v16, 63, v51
	s_bfe_u32 s0, s26, 0x20008
	v_sub_u32_e32 v2, v54, v2
	v_lshlrev_b64 v[40:41], 10, v[14:15]
	v_lshl_add_u32 v47, v13, 2, 0
	v_add_u32_e32 v48, s8, v48
	v_cmp_eq_u32_e64 s[8:9], 0, v16
	s_lshl_b32 s50, s0, 11
	s_lshl_b32 s0, s0, 5
	s_lshl_b32 s26, s27, 1
	v_subrev_u32_e32 v54, 64, v2
	ds_write_b128 v12, v[4:7]
	ds_write_b128 v18, v[8:11] offset:8192
	v_xor_b32_e32 v5, 1, v44
	v_cmp_gt_u32_e64 s[10:11], v5, v44
	v_xor_b32_e32 v5, 2, v44
	v_cmp_gt_u32_e64 s[4:5], v5, v44
	v_xor_b32_e32 v5, 3, v44
	v_and_b32_e32 v4, 7, v51
	v_cmp_gt_u32_e64 s[6:7], v5, v44
	v_lshlrev_b32_e32 v5, 1, v44
	v_bitop3_b32 v6, v44, v51, 7 bitop3:0x78
	v_lshlrev_b32_e32 v49, 4, v6
	v_bitop3_b32 v6, v44, v4, 4 bitop3:0x36
	v_bitop3_b32 v4, v5, v4, 1 bitop3:0x36
	v_lshlrev_b32_e32 v50, 4, v6
	v_bitop3_b32 v6, v5, v51, 7 bitop3:0x78
	v_lshlrev_b32_e32 v52, 4, v4
	v_mov_b32_e32 v4, v3
	v_mov_b32_e32 v5, v3
	v_mov_b32_e32 v2, v3
	v_mov_b64_e32 v[10:11], v[4:5]
	v_mov_b64_e32 v[14:15], v[4:5]
	v_mov_b64_e32 v[18:19], v[4:5]
	v_lshlrev_b32_e32 v51, 4, v6
	s_lshl_b32 s49, s27, 7
	s_or_b32 s0, s0, s26
	v_mov_b64_e32 v[8:9], v[2:3]
	v_mov_b64_e32 v[12:13], v[2:3]
	v_mov_b64_e32 v[16:17], v[2:3]
	v_mov_b64_e32 v[6:7], v[4:5]
	v_mov_b32_e32 v56, 0
	v_lshl_add_u32 v53, v53, 7, 0
	s_add_i32 s26, s0, -1
	s_lshl_b32 s53, s28, 3
	s_or_b32 s51, s49, 64
	s_add_i32 s52, s49, 0x80
	v_mov_b32_e32 v55, 1.0
	s_mov_b32 s54, 0
	v_mov_b64_e32 v[4:5], v[2:3]
	s_mov_b32 s55, 0
	s_and_b64 vcc, exec, s[12:13]
	s_cbranch_vccnz .Lat_nopf
	s_add_i32 s56, s47, 1
	s_mul_i32 s56, s56, s33
	s_add_i32 s56, s56, s38
	s_cmpk_lt_i32 s56, 0x100
	s_cbranch_scc0 .Lat_nopf
	s_mov_b32 s55, 1
	s_mov_b32 s56, 0x400000
	s_mov_b32 s57, 0
	v_lshl_add_u64 v[112:113], v[112:113], 0, s[56:57]
	global_load_dwordx4 v[118:121], v[110:111], off offset:256
	global_load_dwordx4 v[122:125], v[112:113], off
	global_load_dwordx4 v[126:129], v[114:115], off offset:256
	global_load_dwordx4 v[130:133], v[116:117], off offset:320
.Lat_nopf:
	s_lshl_b32 s56, s48, 1
	s_mov_b32 s57, 0
	v_lshl_add_u64 v[142:143], v[40:41], 1, s[24:25]
	v_lshlrev_b32_e32 v144, 3, v44
	v_mov_b32_e32 v145, 0
	v_lshl_add_u64 v[142:143], v[142:143], 0, s[56:57]
	v_lshl_add_u64 v[142:143], v[142:143], 0, v[144:145]
	v_lshl_add_u64 v[142:143], v[142:143], 0, s[20:21]
	global_load_dwordx2 v[134:135], v[142:143], off offset:32
	global_load_dwordx2 v[136:137], v[142:143], off offset:64
	global_load_dwordx2 v[138:139], v[142:143], off
	global_load_dwordx2 v[140:141], v[142:143], off offset:96
	s_waitcnt lgkmcnt(0)
	s_barrier
	s_branch .LBB0_1011

.LBB0_1026:
	s_lshl_b32 s0, s48, 1
	v_lshl_add_u64 v[20:21], v[40:41], 1, s[24:25]
	v_lshlrev_b32_e32 v2, 3, v44
	v_lshl_add_u64 v[20:21], v[20:21], 0, s[0:1]
	v_lshl_add_u64 v[20:21], v[20:21], 0, v[2:3]
	v_lshl_add_u64 v[22:23], v[20:21], 0, s[22:23]
	s_barrier
	s_add_i32 s47, s47, 1
	s_waitcnt vmcnt(2)
	v_lshlrev_b32_e32 v146, 16, v138
	v_and_b32_e32 v147, 0xffff0000, v138
	v_lshlrev_b32_e32 v148, 16, v139
	v_and_b32_e32 v149, 0xffff0000, v139
	v_mul_f32_e32 v146, v8, v146
	v_mul_f32_e32 v147, v9, v147
	v_mul_f32_e32 v148, v10, v148
	v_mul_f32_e32 v149, v11, v149
	v_cvt_pk_bf16_f32 v146, v146, v147
	v_cvt_pk_bf16_f32 v147, v148, v149
	global_store_dwordx2 v[22:23], v[146:147], off
	v_lshlrev_b32_e32 v150, 16, v134
	v_and_b32_e32 v151, 0xffff0000, v134
	v_lshlrev_b32_e32 v152, 16, v135
	v_and_b32_e32 v153, 0xffff0000, v135
	v_mul_f32_e32 v150, v12, v150
	v_mul_f32_e32 v151, v13, v151
	v_mul_f32_e32 v152, v14, v152
	v_mul_f32_e32 v153, v15, v153
	v_cvt_pk_bf16_f32 v150, v150, v151
	v_cvt_pk_bf16_f32 v151, v152, v153
	global_store_dwordx2 v[22:23], v[150:151], off offset:32
	v_lshlrev_b32_e32 v154, 16, v136
	v_and_b32_e32 v155, 0xffff0000, v136
	v_lshlrev_b32_e32 v156, 16, v137
	v_and_b32_e32 v157, 0xffff0000, v137
	v_mul_f32_e32 v154, v16, v154
	v_mul_f32_e32 v155, v17, v155
	v_mul_f32_e32 v156, v18, v156
	v_mul_f32_e32 v157, v19, v157
	v_cvt_pk_bf16_f32 v154, v154, v155
	v_cvt_pk_bf16_f32 v155, v156, v157
	global_store_dwordx2 v[22:23], v[154:155], off offset:64
	v_lshlrev_b32_e32 v158, 16, v140
	v_and_b32_e32 v159, 0xffff0000, v140
	v_lshlrev_b32_e32 v160, 16, v141
	v_and_b32_e32 v161, 0xffff0000, v141
	v_mul_f32_e32 v158, v4, v158
	v_mul_f32_e32 v159, v5, v159
	v_mul_f32_e32 v160, v6, v160
	v_mul_f32_e32 v161, v7, v161
	v_cvt_pk_bf16_f32 v158, v158, v159
	v_cvt_pk_bf16_f32 v159, v160, v161
	global_store_dwordx2 v[22:23], v[158:159], off offset:96
	s_branch .LBB0_1004

.LBB0_1104:
	s_cbranch_execz .LBB0_1070
	v_readlane_b32 s34, v252, 16
	v_readlane_b32 s35, v252, 17
	s_cmp_lt_i32 s35, 11
	s_cbranch_scc1 .LBB0_1144
	s_waitcnt vmcnt(0)
	v_cmp_eq_u32_e32 vcc, 0, v1
	s_waitcnt vmcnt(0) lgkmcnt(0)
	s_barrier
	s_and_saveexec_b64 s[0:1], vcc
	s_cbranch_execz .LBB0_1143
	s_cmp_lg_u32 s101, 0
	s_cbranch_scc1 .Lxl_glob_10
	s_and_b32 s6, s2, 7
	v_mov_b32_e32 v2, 0
	v_mov_b32_e32 v3, 1
	s_nop 3
	s_lshl_b32 s3, s6, 8
	s_add_u32 s4, s86, s3
	s_addc_u32 s5, s87, 0
	s_add_u32 s4, s4, 0x2b00490
	s_addc_u32 s5, s5, 0
	s_mov_b32 s98, 0
	global_atomic_add v2, v3, s[4:5]

.LBB0_1153:
	v_readlane_b32 s34, v252, 16
	v_readlane_b32 s35, v252, 17
	s_cmp_lt_i32 s35, 12
	s_cbranch_scc1 .LBB0_1192
	s_waitcnt vmcnt(0)
	v_cmp_eq_u32_e32 vcc, 0, v1
	s_waitcnt vmcnt(0)
	s_barrier
	s_and_saveexec_b64 s[0:1], vcc
	s_cbranch_execz .LBB0_1191
	s_cmp_lg_u32 s101, 0
	s_cbranch_scc1 .Lxl_glob_11
	s_and_b32 s6, s2, 7
	v_mov_b32_e32 v2, 0
	v_mov_b32_e32 v3, 1
	s_nop 3
	s_lshl_b32 s3, s6, 8
	s_add_u32 s4, s86, s3
	s_addc_u32 s5, s87, 0
	s_add_u32 s4, s4, 0x2b00494
	s_addc_u32 s5, s5, 0
	s_mov_b32 s98, 0
	global_atomic_add v2, v3, s[4:5]

	.amdhsa_kernel _Z4mega6Params
		.amdhsa_group_segment_fixed_size 0
		.amdhsa_private_segment_fixed_size 0
		.amdhsa_kernarg_size 472
		.amdhsa_user_sgpr_count 2
		.amdhsa_user_sgpr_dispatch_ptr 0
		.amdhsa_user_sgpr_queue_ptr 0
		.amdhsa_user_sgpr_kernarg_segment_ptr 1
		.amdhsa_user_sgpr_dispatch_id 0
		.amdhsa_user_sgpr_kernarg_preload_length 0
		.amdhsa_user_sgpr_kernarg_preload_offset 0
		.amdhsa_user_sgpr_private_segment_size 0
		.amdhsa_uses_dynamic_stack 0
		.amdhsa_enable_private_segment 0
		.amdhsa_system_sgpr_workgroup_id_x 1
		.amdhsa_system_sgpr_workgroup_id_y 0
		.amdhsa_system_sgpr_workgroup_id_z 0
		.amdhsa_system_sgpr_workgroup_info 0
		.amdhsa_system_vgpr_workitem_id 2
		.amdhsa_next_free_vgpr 253
		.amdhsa_next_free_sgpr 102
		.amdhsa_accum_offset 256
		.amdhsa_reserve_vcc 1
		.amdhsa_float_round_mode_32 0
		.amdhsa_float_round_mode_16_64 0
		.amdhsa_float_denorm_mode_32 3
		.amdhsa_float_denorm_mode_16_64 3
		.amdhsa_dx10_clamp 1
		.amdhsa_ieee_mode 1
		.amdhsa_fp16_overflow 0
		.amdhsa_tg_split 0
		.amdhsa_exception_fp_ieee_invalid_op 0
		.amdhsa_exception_fp_denorm_src 0
		.amdhsa_exception_fp_ieee_div_zero 0
		.amdhsa_exception_fp_ieee_overflow 0
		.amdhsa_exception_fp_ieee_underflow 0
		.amdhsa_exception_fp_ieee_inexact 0
		.amdhsa_exception_int_div_zero 0
	.end_amdhsa_kernel

amdhsa.kernels:
  - .agpr_count:     0
    .args:
      - .offset:         0
        .size:           216
        .value_kind:     by_value
      - .offset:         216
        .size:           4
        .value_kind:     hidden_block_count_x
      - .offset:         220
        .size:           4
        .value_kind:     hidden_block_count_y
      - .offset:         224
        .size:           4
        .value_kind:     hidden_block_count_z
      - .offset:         228
        .size:           2
        .value_kind:     hidden_group_size_x
      - .offset:         230
        .size:           2
        .value_kind:     hidden_group_size_y
      - .offset:         232
        .size:           2
        .value_kind:     hidden_group_size_z
      - .offset:         234
        .size:           2
        .value_kind:     hidden_remainder_x
      - .offset:         236
        .size:           2
        .value_kind:     hidden_remainder_y
      - .offset:         238
        .size:           2
        .value_kind:     hidden_remainder_z
      - .offset:         256
        .size:           8
        .value_kind:     hidden_global_offset_x
      - .offset:         264
        .size:           8
        .value_kind:     hidden_global_offset_y
      - .offset:         272
        .size:           8
        .value_kind:     hidden_global_offset_z
      - .offset:         280
        .size:           2
        .value_kind:     hidden_grid_dims
      - .offset:         304
        .size:           8
        .value_kind:     hidden_multigrid_sync_arg
      - .offset:         336
        .size:           4
        .value_kind:     hidden_dynamic_lds_size
    .group_segment_fixed_size: 0
    .kernarg_segment_align: 8
    .kernarg_segment_size: 472
    .language:       OpenCL C
    .language_version:
      - 2
      - 0
    .max_flat_workgroup_size: 512
    .name:           _Z4mega6Params
    .private_segment_fixed_size: 0
    .sgpr_count:     108
    .sgpr_spill_count: 108
    .symbol:         _Z4mega6Params.kd
    .uniform_work_group_size: 1
    .uses_dynamic_stack: false
    .vgpr_count:     253
    .vgpr_spill_count: 0
    .wavefront_size: 64
